# v23 + prep-phase bias-vector loop rewritten: 13 consecutive weight rows per wave requested up front, modulation vectors kept in registers, four wave sums side by side
# speedup vs baseline: 1.0089x; 1.0089x over previous
; __device__ __forceinline__ float wave_sum(float v) { v = xadd<1>(v); v = xadd<2>(v); v = xadd<4>(v); v = xadd<8>(v); v = xadd<16>(v); return xadd<32>(v); }
; __device__ __forceinline__ float bf_lo(unsigned w) { return __uint_as_float(w << 16); }
; __device__ __forceinline__ float bf_hi(unsigned w) { return __uint_as_float(w & 0xffff0000u); }
;     __device__ __forceinline__ unsigned char* ws() const { const unsigned long long lo = u(62), hi = u(63); return (unsigned char*)(__attribute__((address_space(1))) unsigned char*)((hi << 32) | lo); }
; __device__ __forceinline__ void prep_phase(const PL& P, int gw, int NGW, int lane) {
;     ...
;     float* bvec = (float*)(ws + WS_BV);
;     for (int it = gw; it < 27648; it += NGW) {
;         int n = it, N = 5632, boff = 0, shoff = 0; const bf16* W = (const bf16*)(ws + WS_W);
;         if (n >= 22016) { n -= 22016; W = (const bf16*)(ws + WS_W + 3 * W_FFN_STRIDE); boff = 88064; shoff = 4 * NMOD + 6144; }
;         else if (n >= 19968) { n -= 19968; W = (const bf16*)(ws + WS_WIN); N = 2048; boff = 79872; shoff = 4 * NMOD + 3072; }
;         else if (n >= 14336) { n -= 14336; W = (const bf16*)(ws + WS_W + 2 * W_FFN_STRIDE); boff = 57344; shoff = 4 * NMOD; }
;         else if (n >= 8704) { n -= 8704; W = (const bf16*)(ws + WS_W + 1 * W_FFN_STRIDE); boff = 34816; shoff = 6144; }
;         else if (n >= 5632) { n -= 5632; W = (const bf16*)(ws + WS_WQKV); N = 3072; boff = 22528; shoff = 3072; }
;         const v4u* wp = (const v4u*)(W + (size_t)n * D + lane * 16); const v4u wa = wp[0], wb = wp[1];
;         const float w[16] = {bf_lo(wa.x), bf_hi(wa.x), bf_lo(wa.y), bf_hi(wa.y), bf_lo(wa.z), bf_hi(wa.z), bf_lo(wa.w), bf_hi(wa.w), bf_lo(wb.x), bf_hi(wb.x), bf_lo(wb.y), bf_hi(wb.y), bf_lo(wb.z), bf_hi(wb.z), bf_lo(wb.w), bf_hi(wb.w)};
; #pragma unroll
;         for (int b = 0; b < 4; ++b) { const f32x4* sp = (const f32x4*)(mod + shoff + (size_t)b * NMOD + lane * 16); float d = 0.f;
; #pragma unroll
;             for (int q = 0; q < 4; ++q) { const f32x4 s4 = sp[q]; d += (s4.x * w[4 * q] + s4.y * w[4 * q + 1]) + (s4.z * w[4 * q + 2] + s4.w * w[4 * q + 3]); }
;             d = wave_sum(d); if (lane == 0) bvec[boff + b * N + n] = d; }
.LBB0_577:
	s_cmpk_gt_i32 s8, 0x6bff
	s_cbranch_scc1 .LBB0_605
	s_add_u32 s3, s6, 0x80000
	s_addc_u32 s9, s7, 0
	s_add_u32 s0, s6, 0x200000
	s_addc_u32 s1, s7, 0
	s_add_u32 s10, s6, 0x4400000
	s_addc_u32 s11, s7, 0
	s_add_u32 s12, s6, 0x1280000
	s_addc_u32 s13, s7, 0
	s_add_u32 s14, s6, 0x2300000
	s_addc_u32 s15, s7, 0
	s_add_u32 s16, s6, 0x4c00000
	s_addc_u32 s17, s7, 0
	s_add_u32 s18, s6, 0x3380000
	v_lshlrev_b32_e32 v2, 4, v227
	v_lshlrev_b32_e32 v176, 6, v227
	s_addc_u32 s19, s7, 0
	v_lshl_add_u64 v[0:1], s[6:7], 0, v[176:177]
	v_cmp_eq_u32_e64 s[6:7], 0, v227
	v_lshlrev_b32_e32 v4, 1, v2
	s_mov_b32 s28, s8
	s_mul_i32 s28, s8, 13
	s_mov_b32 s22, s28
	s_mov_b64 s[24:25], s[0:1]
	s_movk_i32 s29, 0x1600
	s_mov_b32 s20, s28
	s_mov_b32 s23, 0
	s_cmpk_lt_i32 s28, 0x1600
	s_cbranch_scc1 .Lbv_dec1
	s_add_i32 s22, s28, 0xffffea00
	s_mov_b64 s[24:25], s[10:11]
	s_movk_i32 s29, 0xc00
	s_add_i32 s20, s28, 0x4200
	s_mov_b32 s23, 0x3000
	s_cmpk_lt_i32 s28, 0x2200
	s_cbranch_scc1 .Lbv_dec1
	s_add_i32 s22, s28, 0xffffde00
	s_mov_b64 s[24:25], s[12:13]
	s_movk_i32 s29, 0x1600
	s_add_i32 s20, s28, 0x6600
	s_mov_b32 s23, 0x6000
	s_cmpk_lt_i32 s28, 0x3800
	s_cbranch_scc1 .Lbv_dec1
	s_add_i32 s22, s28, 0xffffc800
	s_mov_b64 s[24:25], s[14:15]
	s_movk_i32 s29, 0x1600
	s_add_i32 s20, s28, 0xa800
	s_mov_b32 s23, 0x24000
	s_cmpk_lt_i32 s28, 0x4e00
	s_cbranch_scc1 .Lbv_dec1
	s_add_i32 s22, s28, 0xffffb200
	s_mov_b64 s[24:25], s[16:17]
	s_movk_i32 s29, 0x800
	s_add_i32 s20, s28, 0xea00
	s_mov_b32 s23, 0x27000
	s_cmpk_lt_i32 s28, 0x5600
	s_cbranch_scc1 .Lbv_dec1
	s_add_i32 s22, s28, 0xffffaa00
	s_mov_b64 s[24:25], s[18:19]
	s_movk_i32 s29, 0x1600
	s_add_i32 s20, s28, 0x10200
	s_mov_b32 s23, 0x2a000
.Lbv_dec1:
	s_lshl_b32 s22, s22, 11
	s_add_u32 s24, s24, s22
	s_addc_u32 s25, s25, 0
	s_mov_b32 s21, s23
	s_add_u32 s26, s0, s23
	s_addc_u32 s27, s1, 0
	s_sub_u32 s26, s26, 0x200000
	s_subb_u32 s27, s27, 0
	global_load_dwordx4 v[120:123], v4, s[26:27]
	global_load_dwordx4 v[124:127], v4, s[26:27] offset:16
	global_load_dwordx4 v[128:131], v4, s[26:27] offset:2048
	global_load_dwordx4 v[132:135], v4, s[26:27] offset:2064
	s_add_u32 s26, s26, 0x9000
	s_addc_u32 s27, s27, 0
	global_load_dwordx4 v[136:139], v4, s[26:27]
	global_load_dwordx4 v[140:143], v4, s[26:27] offset:16
	global_load_dwordx4 v[144:147], v4, s[26:27] offset:2048
	global_load_dwordx4 v[148:151], v4, s[26:27] offset:2064
	s_add_u32 s26, s26, 0x9000
	s_addc_u32 s27, s27, 0
	global_load_dwordx4 v[152:155], v4, s[26:27]
	global_load_dwordx4 v[156:159], v4, s[26:27] offset:16
	global_load_dwordx4 v[160:163], v4, s[26:27] offset:2048
	global_load_dwordx4 v[164:167], v4, s[26:27] offset:2064
	s_add_u32 s26, s26, 0x9000
	s_addc_u32 s27, s27, 0
	global_load_dwordx4 v[168:171], v4, s[26:27]
	global_load_dwordx4 v[172:175], v4, s[26:27] offset:16
	global_load_dwordx4 v[182:185], v4, s[26:27] offset:2048
	global_load_dwordx4 v[186:189], v4, s[26:27] offset:2064
	s_mov_b32 s30, 0
.Lbv_pf:
	s_mov_b32 s22, s28
	s_mov_b64 s[24:25], s[0:1]
	s_cmpk_lt_i32 s28, 0x1600
	s_cbranch_scc1 .Lbv_dec2
	s_add_i32 s22, s28, 0xffffea00
	s_mov_b64 s[24:25], s[10:11]
	s_cmpk_lt_i32 s28, 0x2200
	s_cbranch_scc1 .Lbv_dec2
	s_add_i32 s22, s28, 0xffffde00
	s_mov_b64 s[24:25], s[12:13]
	s_cmpk_lt_i32 s28, 0x3800
	s_cbranch_scc1 .Lbv_dec2
	s_add_i32 s22, s28, 0xffffc800
	s_mov_b64 s[24:25], s[14:15]
	s_cmpk_lt_i32 s28, 0x4e00
	s_cbranch_scc1 .Lbv_dec2
	s_add_i32 s22, s28, 0xffffb200
	s_mov_b64 s[24:25], s[16:17]
	s_cmpk_lt_i32 s28, 0x5600
	s_cbranch_scc1 .Lbv_dec2
	s_add_i32 s22, s28, 0xffffaa00
	s_mov_b64 s[24:25], s[18:19]
.Lbv_dec2:
	s_lshl_b32 s22, s22, 11
	s_add_u32 s24, s24, s22
	s_addc_u32 s25, s25, 0
	s_cmp_eq_u32 s30, 0
	s_cbranch_scc1 .Lbv_pf0
	s_cmp_eq_u32 s30, 1
	s_cbranch_scc1 .Lbv_pf1
	s_cmp_eq_u32 s30, 2
	s_cbranch_scc1 .Lbv_pf2
	s_cmp_eq_u32 s30, 3
	s_cbranch_scc1 .Lbv_pf3
	s_cmp_eq_u32 s30, 4
	s_cbranch_scc1 .Lbv_pf4
	s_cmp_eq_u32 s30, 5
	s_cbranch_scc1 .Lbv_pf5
	s_cmp_eq_u32 s30, 6
	s_cbranch_scc1 .Lbv_pf6
	s_cmp_eq_u32 s30, 7
	s_cbranch_scc1 .Lbv_pf7
	s_cmp_eq_u32 s30, 8
	s_cbranch_scc1 .Lbv_pf8
	s_cmp_eq_u32 s30, 9
	s_cbranch_scc1 .Lbv_pf9
	s_cmp_eq_u32 s30, 10
	s_cbranch_scc1 .Lbv_pf10
	s_cmp_eq_u32 s30, 11
	s_cbranch_scc1 .Lbv_pf11
	s_cmp_eq_u32 s30, 12
	s_cbranch_scc1 .Lbv_pf12
	s_branch .Lbv_pf13
.Lbv_pf0:
	global_load_dwordx4 v[8:11], v2, s[24:25]
	global_load_dwordx4 v[12:15], v2, s[24:25] offset:1024
	s_branch .Lbv_pfn
.Lbv_pf1:
	global_load_dwordx4 v[16:19], v2, s[24:25]
	global_load_dwordx4 v[20:23], v2, s[24:25] offset:1024
	s_branch .Lbv_pfn
.Lbv_pf2:
	global_load_dwordx4 v[24:27], v2, s[24:25]
	global_load_dwordx4 v[28:31], v2, s[24:25] offset:1024
	s_branch .Lbv_pfn
.Lbv_pf3:
	global_load_dwordx4 v[32:35], v2, s[24:25]
	global_load_dwordx4 v[36:39], v2, s[24:25] offset:1024
	s_branch .Lbv_pfn
.Lbv_pf4:
	global_load_dwordx4 v[40:43], v2, s[24:25]
	global_load_dwordx4 v[44:47], v2, s[24:25] offset:1024
	s_branch .Lbv_pfn
.Lbv_pf5:
	global_load_dwordx4 v[48:51], v2, s[24:25]
	global_load_dwordx4 v[52:55], v2, s[24:25] offset:1024
	s_branch .Lbv_pfn
.Lbv_pf6:
	global_load_dwordx4 v[56:59], v2, s[24:25]
	global_load_dwordx4 v[60:63], v2, s[24:25] offset:1024
	s_branch .Lbv_pfn
.Lbv_pf7:
	global_load_dwordx4 v[64:67], v2, s[24:25]
	global_load_dwordx4 v[68:71], v2, s[24:25] offset:1024
	s_branch .Lbv_pfn
.Lbv_pf8:
	global_load_dwordx4 v[72:75], v2, s[24:25]
	global_load_dwordx4 v[76:79], v2, s[24:25] offset:1024
	s_branch .Lbv_pfn
.Lbv_pf9:
	global_load_dwordx4 v[80:83], v2, s[24:25]
	global_load_dwordx4 v[84:87], v2, s[24:25] offset:1024
	s_branch .Lbv_pfn
; __device__ __forceinline__ float wave_sum(float v) { v = xadd<1>(v); v = xadd<2>(v); v = xadd<4>(v); v = xadd<8>(v); v = xadd<16>(v); return xadd<32>(v); }
; __device__ __forceinline__ float bf_lo(unsigned w) { return __uint_as_float(w << 16); }
; __device__ __forceinline__ float bf_hi(unsigned w) { return __uint_as_float(w & 0xffff0000u); }
;     __device__ __forceinline__ unsigned char* ws() const { const unsigned long long lo = u(62), hi = u(63); return (unsigned char*)(__attribute__((address_space(1))) unsigned char*)((hi << 32) | lo); }
; __device__ __forceinline__ void prep_phase(const PL& P, int gw, int NGW, int lane) {
;     ...
;     for (int it = gw; it < 27648; it += NGW) {
;         int n = it, N = 5632, boff = 0, shoff = 0; const bf16* W = (const bf16*)(ws + WS_W);
;         if (n >= 22016) { n -= 22016; W = (const bf16*)(ws + WS_W + 3 * W_FFN_STRIDE); boff = 88064; shoff = 4 * NMOD + 6144; }
;         else if (n >= 19968) { n -= 19968; W = (const bf16*)(ws + WS_WIN); N = 2048; boff = 79872; shoff = 4 * NMOD + 3072; }
;         else if (n >= 14336) { n -= 14336; W = (const bf16*)(ws + WS_W + 2 * W_FFN_STRIDE); boff = 57344; shoff = 4 * NMOD; }
;         else if (n >= 8704) { n -= 8704; W = (const bf16*)(ws + WS_W + 1 * W_FFN_STRIDE); boff = 34816; shoff = 6144; }
;         else if (n >= 5632) { n -= 5632; W = (const bf16*)(ws + WS_WQKV); N = 3072; boff = 22528; shoff = 3072; }
;         const v4u* wp = (const v4u*)(W + (size_t)n * D + lane * 16); const v4u wa = wp[0], wb = wp[1];
;         const float w[16] = {bf_lo(wa.x), bf_hi(wa.x), bf_lo(wa.y), bf_hi(wa.y), bf_lo(wa.z), bf_hi(wa.z), bf_lo(wa.w), bf_hi(wa.w), bf_lo(wb.x), bf_hi(wb.x), bf_lo(wb.y), bf_hi(wb.y), bf_lo(wb.z), bf_hi(wb.z), bf_lo(wb.w), bf_hi(wb.w)};
; #pragma unroll
;         for (int b = 0; b < 4; ++b) { const f32x4* sp = (const f32x4*)(mod + shoff + (size_t)b * NMOD + lane * 16); float d = 0.f;
; #pragma unroll
;             for (int q = 0; q < 4; ++q) { const f32x4 s4 = sp[q]; d += (s4.x * w[4 * q] + s4.y * w[4 * q + 1]) + (s4.z * w[4 * q + 2] + s4.w * w[4 * q + 3]); }
;             d = wave_sum(d); if (lane == 0) bvec[boff + b * N + n] = d; }
.Lbv_pf10:
	global_load_dwordx4 v[88:91], v2, s[24:25]
	global_load_dwordx4 v[92:95], v2, s[24:25] offset:1024
	s_branch .Lbv_pfn
.Lbv_pf11:
	global_load_dwordx4 v[96:99], v2, s[24:25]
	global_load_dwordx4 v[100:103], v2, s[24:25] offset:1024
	s_branch .Lbv_pfn
.Lbv_pf12:
	global_load_dwordx4 v[104:107], v2, s[24:25]
	global_load_dwordx4 v[108:111], v2, s[24:25] offset:1024
	s_branch .Lbv_pfn
.Lbv_pf13:
	global_load_dwordx4 v[112:115], v2, s[24:25]
	global_load_dwordx4 v[116:119], v2, s[24:25] offset:1024
	s_branch .Lbv_rows
.Lbv_pfn:
	s_add_i32 s30, s30, 1
	s_add_i32 s28, s28, 1
	s_cmp_lt_u32 s30, 13
	s_cbranch_scc1 .Lbv_pf
	s_add_i32 s28, s28, -1
	s_cmpk_ge_u32 s8, 0x400
	s_cbranch_scc1 .Lbv_pf
	s_add_i32 s28, s8, 0x6800
	s_branch .Lbv_pf
.Lbv_rows:
	s_mul_i32 s28, s8, 13
	s_mov_b32 s30, 0
.Lbv_row:
	s_mov_b32 s22, s28
	s_mov_b64 s[24:25], s[0:1]
	s_movk_i32 s29, 0x1600
	s_mov_b32 s20, s28
	s_mov_b32 s23, 0
	s_cmpk_lt_i32 s28, 0x1600
	s_cbranch_scc1 .Lbv_dec3
	s_add_i32 s22, s28, 0xffffea00
	s_mov_b64 s[24:25], s[10:11]
	s_movk_i32 s29, 0xc00
	s_add_i32 s20, s28, 0x4200
	s_mov_b32 s23, 0x3000
	s_cmpk_lt_i32 s28, 0x2200
	s_cbranch_scc1 .Lbv_dec3
	s_add_i32 s22, s28, 0xffffde00
	s_mov_b64 s[24:25], s[12:13]
	s_movk_i32 s29, 0x1600
	s_add_i32 s20, s28, 0x6600
	s_mov_b32 s23, 0x6000
	s_cmpk_lt_i32 s28, 0x3800
	s_cbranch_scc1 .Lbv_dec3
	s_add_i32 s22, s28, 0xffffc800
	s_mov_b64 s[24:25], s[14:15]
	s_movk_i32 s29, 0x1600
	s_add_i32 s20, s28, 0xa800
	s_mov_b32 s23, 0x24000
	s_cmpk_lt_i32 s28, 0x4e00
	s_cbranch_scc1 .Lbv_dec3
	s_add_i32 s22, s28, 0xffffb200
	s_mov_b64 s[24:25], s[16:17]
	s_movk_i32 s29, 0x800
	s_add_i32 s20, s28, 0xea00
	s_mov_b32 s23, 0x27000
	s_cmpk_lt_i32 s28, 0x5600
	s_cbranch_scc1 .Lbv_dec3
	s_add_i32 s22, s28, 0xffffaa00
	s_mov_b64 s[24:25], s[18:19]
	s_movk_i32 s29, 0x1600
	s_add_i32 s20, s28, 0x10200
	s_mov_b32 s23, 0x2a000
.Lbv_dec3:
	s_lshl_b32 s22, s22, 11
	s_add_u32 s24, s24, s22
	s_addc_u32 s25, s25, 0
	s_cmp_eq_u32 s23, s21
	s_cbranch_scc1 .Lbv_same
	s_mov_b32 s21, s23
	s_add_u32 s26, s0, s23
	s_addc_u32 s27, s1, 0
	s_sub_u32 s26, s26, 0x200000
	s_subb_u32 s27, s27, 0
	global_load_dwordx4 v[120:123], v4, s[26:27]
	global_load_dwordx4 v[124:127], v4, s[26:27] offset:16
	global_load_dwordx4 v[128:131], v4, s[26:27] offset:2048
	global_load_dwordx4 v[132:135], v4, s[26:27] offset:2064
	s_add_u32 s26, s26, 0x9000
	s_addc_u32 s27, s27, 0
	global_load_dwordx4 v[136:139], v4, s[26:27]
	global_load_dwordx4 v[140:143], v4, s[26:27] offset:16
	global_load_dwordx4 v[144:147], v4, s[26:27] offset:2048
	global_load_dwordx4 v[148:151], v4, s[26:27] offset:2064
	s_add_u32 s26, s26, 0x9000
	s_addc_u32 s27, s27, 0
	global_load_dwordx4 v[152:155], v4, s[26:27]
	global_load_dwordx4 v[156:159], v4, s[26:27] offset:16
	global_load_dwordx4 v[160:163], v4, s[26:27] offset:2048
	global_load_dwordx4 v[164:167], v4, s[26:27] offset:2064
	s_add_u32 s26, s26, 0x9000
	s_addc_u32 s27, s27, 0
	global_load_dwordx4 v[168:171], v4, s[26:27]
	global_load_dwordx4 v[172:175], v4, s[26:27] offset:16
	global_load_dwordx4 v[182:185], v4, s[26:27] offset:2048
	global_load_dwordx4 v[186:189], v4, s[26:27] offset:2064
	s_waitcnt vmcnt(0)
.Lbv_same:
	s_cmp_eq_u32 s30, 0
	s_cbranch_scc1 .Lbv_u0
	s_cmp_eq_u32 s30, 1
	s_cbranch_scc1 .Lbv_u1
	s_cmp_eq_u32 s30, 2
	s_cbranch_scc1 .Lbv_u2
	s_cmp_eq_u32 s30, 3
	s_cbranch_scc1 .Lbv_u3
	s_cmp_eq_u32 s30, 4
	s_cbranch_scc1 .Lbv_u4
	s_cmp_eq_u32 s30, 5
	s_cbranch_scc1 .Lbv_u5
	s_cmp_eq_u32 s30, 6
	s_cbranch_scc1 .Lbv_u6
	s_cmp_eq_u32 s30, 7
	s_cbranch_scc1 .Lbv_u7
	s_cmp_eq_u32 s30, 8
	s_cbranch_scc1 .Lbv_u8
	s_cmp_eq_u32 s30, 9
	s_cbranch_scc1 .Lbv_u9
	s_cmp_eq_u32 s30, 10
	s_cbranch_scc1 .Lbv_u10
	s_cmp_eq_u32 s30, 11
	s_cbranch_scc1 .Lbv_u11
	s_cmp_eq_u32 s30, 12
	s_cbranch_scc1 .Lbv_u12
	s_branch .Lbv_u13
.Lbv_u0:
	s_waitcnt vmcnt(26)
	v_lshlrev_b32_e32 v190, 16, v8
	v_and_b32_e32 v191, 0xffff0000, v8
	v_lshlrev_b32_e32 v192, 16, v9
	v_and_b32_e32 v193, 0xffff0000, v9
	v_lshlrev_b32_e32 v194, 16, v10
	v_and_b32_e32 v195, 0xffff0000, v10
	v_lshlrev_b32_e32 v196, 16, v11
	v_and_b32_e32 v197, 0xffff0000, v11
	v_lshlrev_b32_e32 v198, 16, v12
	v_and_b32_e32 v199, 0xffff0000, v12
	v_lshlrev_b32_e32 v200, 16, v13
	v_and_b32_e32 v201, 0xffff0000, v13
	v_lshlrev_b32_e32 v202, 16, v14
	v_and_b32_e32 v203, 0xffff0000, v14
	v_lshlrev_b32_e32 v204, 16, v15
	v_and_b32_e32 v205, 0xffff0000, v15
	s_branch .Lbv_dot
.Lbv_u1:
	s_waitcnt vmcnt(28)
	v_lshlrev_b32_e32 v190, 16, v16
	v_and_b32_e32 v191, 0xffff0000, v16
	v_lshlrev_b32_e32 v192, 16, v17
	v_and_b32_e32 v193, 0xffff0000, v17
	v_lshlrev_b32_e32 v194, 16, v18
	v_and_b32_e32 v195, 0xffff0000, v18
	v_lshlrev_b32_e32 v196, 16, v19
	v_and_b32_e32 v197, 0xffff0000, v19
	v_lshlrev_b32_e32 v198, 16, v20
	v_and_b32_e32 v199, 0xffff0000, v20
	v_lshlrev_b32_e32 v200, 16, v21
	v_and_b32_e32 v201, 0xffff0000, v21
	v_lshlrev_b32_e32 v202, 16, v22
	v_and_b32_e32 v203, 0xffff0000, v22
	v_lshlrev_b32_e32 v204, 16, v23
	v_and_b32_e32 v205, 0xffff0000, v23
	s_branch .Lbv_dot
.Lbv_u2:
	s_waitcnt vmcnt(30)
	v_lshlrev_b32_e32 v190, 16, v24
	v_and_b32_e32 v191, 0xffff0000, v24
	v_lshlrev_b32_e32 v192, 16, v25
	v_and_b32_e32 v193, 0xffff0000, v25
	v_lshlrev_b32_e32 v194, 16, v26
	v_and_b32_e32 v195, 0xffff0000, v26
	v_lshlrev_b32_e32 v196, 16, v27
	v_and_b32_e32 v197, 0xffff0000, v27
	v_lshlrev_b32_e32 v198, 16, v28
	v_and_b32_e32 v199, 0xffff0000, v28
	v_lshlrev_b32_e32 v200, 16, v29
	v_and_b32_e32 v201, 0xffff0000, v29
	v_lshlrev_b32_e32 v202, 16, v30
	v_and_b32_e32 v203, 0xffff0000, v30
	v_lshlrev_b32_e32 v204, 16, v31
	v_and_b32_e32 v205, 0xffff0000, v31
	s_branch .Lbv_dot
; __device__ __forceinline__ float bf_lo(unsigned w) { return __uint_as_float(w << 16); }
; __device__ __forceinline__ float bf_hi(unsigned w) { return __uint_as_float(w & 0xffff0000u); }
; __device__ __forceinline__ void prep_phase(const PL& P, int gw, int NGW, int lane) {
;     ...
;         const v4u* wp = (const v4u*)(W + (size_t)n * D + lane * 16); const v4u wa = wp[0], wb = wp[1];
;         const float w[16] = {bf_lo(wa.x), bf_hi(wa.x), bf_lo(wa.y), bf_hi(wa.y), bf_lo(wa.z), bf_hi(wa.z), bf_lo(wa.w), bf_hi(wa.w), bf_lo(wb.x), bf_hi(wb.x), bf_lo(wb.y), bf_hi(wb.y), bf_lo(wb.z), bf_hi(wb.z), bf_lo(wb.w), bf_hi(wb.w)};
.Lbv_u3:
	s_waitcnt vmcnt(32)
	v_lshlrev_b32_e32 v190, 16, v32
	v_and_b32_e32 v191, 0xffff0000, v32
	v_lshlrev_b32_e32 v192, 16, v33
	v_and_b32_e32 v193, 0xffff0000, v33
	v_lshlrev_b32_e32 v194, 16, v34
	v_and_b32_e32 v195, 0xffff0000, v34
	v_lshlrev_b32_e32 v196, 16, v35
	v_and_b32_e32 v197, 0xffff0000, v35
	v_lshlrev_b32_e32 v198, 16, v36
	v_and_b32_e32 v199, 0xffff0000, v36
	v_lshlrev_b32_e32 v200, 16, v37
	v_and_b32_e32 v201, 0xffff0000, v37
	v_lshlrev_b32_e32 v202, 16, v38
	v_and_b32_e32 v203, 0xffff0000, v38
	v_lshlrev_b32_e32 v204, 16, v39
	v_and_b32_e32 v205, 0xffff0000, v39
	s_branch .Lbv_dot
.Lbv_u4:
	s_waitcnt vmcnt(34)
	v_lshlrev_b32_e32 v190, 16, v40
	v_and_b32_e32 v191, 0xffff0000, v40
	v_lshlrev_b32_e32 v192, 16, v41
	v_and_b32_e32 v193, 0xffff0000, v41
	v_lshlrev_b32_e32 v194, 16, v42
	v_and_b32_e32 v195, 0xffff0000, v42
	v_lshlrev_b32_e32 v196, 16, v43
	v_and_b32_e32 v197, 0xffff0000, v43
	v_lshlrev_b32_e32 v198, 16, v44
	v_and_b32_e32 v199, 0xffff0000, v44
	v_lshlrev_b32_e32 v200, 16, v45
	v_and_b32_e32 v201, 0xffff0000, v45
	v_lshlrev_b32_e32 v202, 16, v46
	v_and_b32_e32 v203, 0xffff0000, v46
	v_lshlrev_b32_e32 v204, 16, v47
	v_and_b32_e32 v205, 0xffff0000, v47
	s_branch .Lbv_dot
.Lbv_u5:
	s_waitcnt vmcnt(36)
	v_lshlrev_b32_e32 v190, 16, v48
	v_and_b32_e32 v191, 0xffff0000, v48
	v_lshlrev_b32_e32 v192, 16, v49
	v_and_b32_e32 v193, 0xffff0000, v49
	v_lshlrev_b32_e32 v194, 16, v50
	v_and_b32_e32 v195, 0xffff0000, v50
	v_lshlrev_b32_e32 v196, 16, v51
	v_and_b32_e32 v197, 0xffff0000, v51
	v_lshlrev_b32_e32 v198, 16, v52
	v_and_b32_e32 v199, 0xffff0000, v52
	v_lshlrev_b32_e32 v200, 16, v53
	v_and_b32_e32 v201, 0xffff0000, v53
	v_lshlrev_b32_e32 v202, 16, v54
	v_and_b32_e32 v203, 0xffff0000, v54
	v_lshlrev_b32_e32 v204, 16, v55
	v_and_b32_e32 v205, 0xffff0000, v55
	s_branch .Lbv_dot
.Lbv_u6:
	s_waitcnt vmcnt(38)
	v_lshlrev_b32_e32 v190, 16, v56
	v_and_b32_e32 v191, 0xffff0000, v56
	v_lshlrev_b32_e32 v192, 16, v57
	v_and_b32_e32 v193, 0xffff0000, v57
	v_lshlrev_b32_e32 v194, 16, v58
	v_and_b32_e32 v195, 0xffff0000, v58
	v_lshlrev_b32_e32 v196, 16, v59
	v_and_b32_e32 v197, 0xffff0000, v59
	v_lshlrev_b32_e32 v198, 16, v60
	v_and_b32_e32 v199, 0xffff0000, v60
	v_lshlrev_b32_e32 v200, 16, v61
	v_and_b32_e32 v201, 0xffff0000, v61
	v_lshlrev_b32_e32 v202, 16, v62
	v_and_b32_e32 v203, 0xffff0000, v62
	v_lshlrev_b32_e32 v204, 16, v63
	v_and_b32_e32 v205, 0xffff0000, v63
	s_branch .Lbv_dot
.Lbv_u7:
	s_waitcnt vmcnt(40)
	v_lshlrev_b32_e32 v190, 16, v64
	v_and_b32_e32 v191, 0xffff0000, v64
	v_lshlrev_b32_e32 v192, 16, v65
	v_and_b32_e32 v193, 0xffff0000, v65
	v_lshlrev_b32_e32 v194, 16, v66
	v_and_b32_e32 v195, 0xffff0000, v66
	v_lshlrev_b32_e32 v196, 16, v67
	v_and_b32_e32 v197, 0xffff0000, v67
	v_lshlrev_b32_e32 v198, 16, v68
	v_and_b32_e32 v199, 0xffff0000, v68
	v_lshlrev_b32_e32 v200, 16, v69
	v_and_b32_e32 v201, 0xffff0000, v69
	v_lshlrev_b32_e32 v202, 16, v70
	v_and_b32_e32 v203, 0xffff0000, v70
	v_lshlrev_b32_e32 v204, 16, v71
	v_and_b32_e32 v205, 0xffff0000, v71
	s_branch .Lbv_dot
.Lbv_u8:
	s_waitcnt vmcnt(42)
	v_lshlrev_b32_e32 v190, 16, v72
	v_and_b32_e32 v191, 0xffff0000, v72
	v_lshlrev_b32_e32 v192, 16, v73
	v_and_b32_e32 v193, 0xffff0000, v73
	v_lshlrev_b32_e32 v194, 16, v74
	v_and_b32_e32 v195, 0xffff0000, v74
	v_lshlrev_b32_e32 v196, 16, v75
	v_and_b32_e32 v197, 0xffff0000, v75
	v_lshlrev_b32_e32 v198, 16, v76
	v_and_b32_e32 v199, 0xffff0000, v76
	v_lshlrev_b32_e32 v200, 16, v77
	v_and_b32_e32 v201, 0xffff0000, v77
	v_lshlrev_b32_e32 v202, 16, v78
	v_and_b32_e32 v203, 0xffff0000, v78
	v_lshlrev_b32_e32 v204, 16, v79
	v_and_b32_e32 v205, 0xffff0000, v79
	s_branch .Lbv_dot
.Lbv_u9:
	s_waitcnt vmcnt(44)
	v_lshlrev_b32_e32 v190, 16, v80
	v_and_b32_e32 v191, 0xffff0000, v80
	v_lshlrev_b32_e32 v192, 16, v81
	v_and_b32_e32 v193, 0xffff0000, v81
	v_lshlrev_b32_e32 v194, 16, v82
	v_and_b32_e32 v195, 0xffff0000, v82
	v_lshlrev_b32_e32 v196, 16, v83
	v_and_b32_e32 v197, 0xffff0000, v83
	v_lshlrev_b32_e32 v198, 16, v84
	v_and_b32_e32 v199, 0xffff0000, v84
	v_lshlrev_b32_e32 v200, 16, v85
	v_and_b32_e32 v201, 0xffff0000, v85
	v_lshlrev_b32_e32 v202, 16, v86
	v_and_b32_e32 v203, 0xffff0000, v86
	v_lshlrev_b32_e32 v204, 16, v87
	v_and_b32_e32 v205, 0xffff0000, v87
	s_branch .Lbv_dot
.Lbv_u10:
	s_waitcnt vmcnt(46)
	v_lshlrev_b32_e32 v190, 16, v88
	v_and_b32_e32 v191, 0xffff0000, v88
	v_lshlrev_b32_e32 v192, 16, v89
	v_and_b32_e32 v193, 0xffff0000, v89
	v_lshlrev_b32_e32 v194, 16, v90
	v_and_b32_e32 v195, 0xffff0000, v90
	v_lshlrev_b32_e32 v196, 16, v91
	v_and_b32_e32 v197, 0xffff0000, v91
	v_lshlrev_b32_e32 v198, 16, v92
	v_and_b32_e32 v199, 0xffff0000, v92
	v_lshlrev_b32_e32 v200, 16, v93
	v_and_b32_e32 v201, 0xffff0000, v93
	v_lshlrev_b32_e32 v202, 16, v94
	v_and_b32_e32 v203, 0xffff0000, v94
	v_lshlrev_b32_e32 v204, 16, v95
	v_and_b32_e32 v205, 0xffff0000, v95
	s_branch .Lbv_dot
.Lbv_u11:
	s_waitcnt vmcnt(48)
	v_lshlrev_b32_e32 v190, 16, v96
	v_and_b32_e32 v191, 0xffff0000, v96
	v_lshlrev_b32_e32 v192, 16, v97
	v_and_b32_e32 v193, 0xffff0000, v97
	v_lshlrev_b32_e32 v194, 16, v98
	v_and_b32_e32 v195, 0xffff0000, v98
	v_lshlrev_b32_e32 v196, 16, v99
	v_and_b32_e32 v197, 0xffff0000, v99
	v_lshlrev_b32_e32 v198, 16, v100
	v_and_b32_e32 v199, 0xffff0000, v100
	v_lshlrev_b32_e32 v200, 16, v101
	v_and_b32_e32 v201, 0xffff0000, v101
	v_lshlrev_b32_e32 v202, 16, v102
	v_and_b32_e32 v203, 0xffff0000, v102
	v_lshlrev_b32_e32 v204, 16, v103
	v_and_b32_e32 v205, 0xffff0000, v103
	s_branch .Lbv_dot
; __device__ __forceinline__ float wave_sum(float v) { v = xadd<1>(v); v = xadd<2>(v); v = xadd<4>(v); v = xadd<8>(v); v = xadd<16>(v); return xadd<32>(v); }
; __device__ __forceinline__ float bf_lo(unsigned w) { return __uint_as_float(w << 16); }
; __device__ __forceinline__ float bf_hi(unsigned w) { return __uint_as_float(w & 0xffff0000u); }
;     __device__ __forceinline__ unsigned char* ws() const { const unsigned long long lo = u(62), hi = u(63); return (unsigned char*)(__attribute__((address_space(1))) unsigned char*)((hi << 32) | lo); }
; __device__ __forceinline__ void prep_phase(const PL& P, int gw, int NGW, int lane) {
;     ...
;     for (int it = gw; it < 27648; it += NGW) {
;         int n = it, N = 5632, boff = 0, shoff = 0; const bf16* W = (const bf16*)(ws + WS_W);
;         if (n >= 22016) { n -= 22016; W = (const bf16*)(ws + WS_W + 3 * W_FFN_STRIDE); boff = 88064; shoff = 4 * NMOD + 6144; }
;         else if (n >= 19968) { n -= 19968; W = (const bf16*)(ws + WS_WIN); N = 2048; boff = 79872; shoff = 4 * NMOD + 3072; }
;         else if (n >= 14336) { n -= 14336; W = (const bf16*)(ws + WS_W + 2 * W_FFN_STRIDE); boff = 57344; shoff = 4 * NMOD; }
;         else if (n >= 8704) { n -= 8704; W = (const bf16*)(ws + WS_W + 1 * W_FFN_STRIDE); boff = 34816; shoff = 6144; }
;         else if (n >= 5632) { n -= 5632; W = (const bf16*)(ws + WS_WQKV); N = 3072; boff = 22528; shoff = 3072; }
;         const v4u* wp = (const v4u*)(W + (size_t)n * D + lane * 16); const v4u wa = wp[0], wb = wp[1];
;         const float w[16] = {bf_lo(wa.x), bf_hi(wa.x), bf_lo(wa.y), bf_hi(wa.y), bf_lo(wa.z), bf_hi(wa.z), bf_lo(wa.w), bf_hi(wa.w), bf_lo(wb.x), bf_hi(wb.x), bf_lo(wb.y), bf_hi(wb.y), bf_lo(wb.z), bf_hi(wb.z), bf_lo(wb.w), bf_hi(wb.w)};
; #pragma unroll
;         for (int b = 0; b < 4; ++b) { const f32x4* sp = (const f32x4*)(mod + shoff + (size_t)b * NMOD + lane * 16); float d = 0.f;
; #pragma unroll
;             for (int q = 0; q < 4; ++q) { const f32x4 s4 = sp[q]; d += (s4.x * w[4 * q] + s4.y * w[4 * q + 1]) + (s4.z * w[4 * q + 2] + s4.w * w[4 * q + 3]); }
;             d = wave_sum(d); if (lane == 0) bvec[boff + b * N + n] = d; }
.Lbv_u12:
	s_waitcnt vmcnt(50)
	v_lshlrev_b32_e32 v190, 16, v104
	v_and_b32_e32 v191, 0xffff0000, v104
	v_lshlrev_b32_e32 v192, 16, v105
	v_and_b32_e32 v193, 0xffff0000, v105
	v_lshlrev_b32_e32 v194, 16, v106
	v_and_b32_e32 v195, 0xffff0000, v106
	v_lshlrev_b32_e32 v196, 16, v107
	v_and_b32_e32 v197, 0xffff0000, v107
	v_lshlrev_b32_e32 v198, 16, v108
	v_and_b32_e32 v199, 0xffff0000, v108
	v_lshlrev_b32_e32 v200, 16, v109
	v_and_b32_e32 v201, 0xffff0000, v109
	v_lshlrev_b32_e32 v202, 16, v110
	v_and_b32_e32 v203, 0xffff0000, v110
	v_lshlrev_b32_e32 v204, 16, v111
	v_and_b32_e32 v205, 0xffff0000, v111
	s_branch .Lbv_dot
.Lbv_u13:
	s_waitcnt vmcnt(52)
	v_lshlrev_b32_e32 v190, 16, v112
	v_and_b32_e32 v191, 0xffff0000, v112
	v_lshlrev_b32_e32 v192, 16, v113
	v_and_b32_e32 v193, 0xffff0000, v113
	v_lshlrev_b32_e32 v194, 16, v114
	v_and_b32_e32 v195, 0xffff0000, v114
	v_lshlrev_b32_e32 v196, 16, v115
	v_and_b32_e32 v197, 0xffff0000, v115
	v_lshlrev_b32_e32 v198, 16, v116
	v_and_b32_e32 v199, 0xffff0000, v116
	v_lshlrev_b32_e32 v200, 16, v117
	v_and_b32_e32 v201, 0xffff0000, v117
	v_lshlrev_b32_e32 v202, 16, v118
	v_and_b32_e32 v203, 0xffff0000, v118
	v_lshlrev_b32_e32 v204, 16, v119
	v_and_b32_e32 v205, 0xffff0000, v119
.Lbv_dot:
	v_mul_f32_e32 v206, v120, v190
	v_mul_f32_e32 v207, v136, v190
	v_mul_f32_e32 v208, v152, v190
	v_mul_f32_e32 v209, v168, v190
	v_fmac_f32_e32 v206, v121, v191
	v_fmac_f32_e32 v207, v137, v191
	v_fmac_f32_e32 v208, v153, v191
	v_fmac_f32_e32 v209, v169, v191
	v_fmac_f32_e32 v206, v122, v192
	v_fmac_f32_e32 v207, v138, v192
	v_fmac_f32_e32 v208, v154, v192
	v_fmac_f32_e32 v209, v170, v192
	v_fmac_f32_e32 v206, v123, v193
	v_fmac_f32_e32 v207, v139, v193
	v_fmac_f32_e32 v208, v155, v193
	v_fmac_f32_e32 v209, v171, v193
	v_fmac_f32_e32 v206, v124, v194
	v_fmac_f32_e32 v207, v140, v194
	v_fmac_f32_e32 v208, v156, v194
	v_fmac_f32_e32 v209, v172, v194
	v_fmac_f32_e32 v206, v125, v195
	v_fmac_f32_e32 v207, v141, v195
	v_fmac_f32_e32 v208, v157, v195
	v_fmac_f32_e32 v209, v173, v195
	v_fmac_f32_e32 v206, v126, v196
	v_fmac_f32_e32 v207, v142, v196
	v_fmac_f32_e32 v208, v158, v196
	v_fmac_f32_e32 v209, v174, v196
	v_fmac_f32_e32 v206, v127, v197
	v_fmac_f32_e32 v207, v143, v197
	v_fmac_f32_e32 v208, v159, v197
	v_fmac_f32_e32 v209, v175, v197
	v_fmac_f32_e32 v206, v128, v198
	v_fmac_f32_e32 v207, v144, v198
	v_fmac_f32_e32 v208, v160, v198
	v_fmac_f32_e32 v209, v182, v198
	v_fmac_f32_e32 v206, v129, v199
	v_fmac_f32_e32 v207, v145, v199
	v_fmac_f32_e32 v208, v161, v199
	v_fmac_f32_e32 v209, v183, v199
	v_fmac_f32_e32 v206, v130, v200
	v_fmac_f32_e32 v207, v146, v200
	v_fmac_f32_e32 v208, v162, v200
	v_fmac_f32_e32 v209, v184, v200
	v_fmac_f32_e32 v206, v131, v201
	v_fmac_f32_e32 v207, v147, v201
	v_fmac_f32_e32 v208, v163, v201
	v_fmac_f32_e32 v209, v185, v201
	v_fmac_f32_e32 v206, v132, v202
	v_fmac_f32_e32 v207, v148, v202
	v_fmac_f32_e32 v208, v164, v202
	v_fmac_f32_e32 v209, v186, v202
	v_fmac_f32_e32 v206, v133, v203
	v_fmac_f32_e32 v207, v149, v203
	v_fmac_f32_e32 v208, v165, v203
	v_fmac_f32_e32 v209, v187, v203
	v_fmac_f32_e32 v206, v134, v204
	v_fmac_f32_e32 v207, v150, v204
	v_fmac_f32_e32 v208, v166, v204
	v_fmac_f32_e32 v209, v188, v204
	v_fmac_f32_e32 v206, v135, v205
	v_fmac_f32_e32 v207, v151, v205
	v_fmac_f32_e32 v208, v167, v205
	v_fmac_f32_e32 v209, v189, v205
	ds_swizzle_b32 v0, v206 offset:swizzle(SWAP,1)
	ds_swizzle_b32 v1, v207 offset:swizzle(SWAP,1)
	ds_swizzle_b32 v3, v208 offset:swizzle(SWAP,1)
	ds_swizzle_b32 v5, v209 offset:swizzle(SWAP,1)
	s_waitcnt lgkmcnt(0)
	v_add_f32_e32 v206, v206, v0
	v_add_f32_e32 v207, v207, v1
	v_add_f32_e32 v208, v208, v3
	v_add_f32_e32 v209, v209, v5
	ds_swizzle_b32 v0, v206 offset:swizzle(SWAP,2)
	ds_swizzle_b32 v1, v207 offset:swizzle(SWAP,2)
	ds_swizzle_b32 v3, v208 offset:swizzle(SWAP,2)
	ds_swizzle_b32 v5, v209 offset:swizzle(SWAP,2)
	s_waitcnt lgkmcnt(0)
	v_add_f32_e32 v206, v206, v0
	v_add_f32_e32 v207, v207, v1
	v_add_f32_e32 v208, v208, v3
	v_add_f32_e32 v209, v209, v5
	ds_swizzle_b32 v0, v206 offset:swizzle(SWAP,4)
	ds_swizzle_b32 v1, v207 offset:swizzle(SWAP,4)
	ds_swizzle_b32 v3, v208 offset:swizzle(SWAP,4)
	ds_swizzle_b32 v5, v209 offset:swizzle(SWAP,4)
	s_waitcnt lgkmcnt(0)
	v_add_f32_e32 v206, v206, v0
	v_add_f32_e32 v207, v207, v1
	v_add_f32_e32 v208, v208, v3
	v_add_f32_e32 v209, v209, v5
	ds_swizzle_b32 v0, v206 offset:swizzle(SWAP,8)
	ds_swizzle_b32 v1, v207 offset:swizzle(SWAP,8)
	ds_swizzle_b32 v3, v208 offset:swizzle(SWAP,8)
	ds_swizzle_b32 v5, v209 offset:swizzle(SWAP,8)
	s_waitcnt lgkmcnt(0)
	v_add_f32_e32 v206, v206, v0
	v_add_f32_e32 v207, v207, v1
	v_add_f32_e32 v208, v208, v3
	v_add_f32_e32 v209, v209, v5
	ds_swizzle_b32 v0, v206 offset:swizzle(SWAP,16)
	ds_swizzle_b32 v1, v207 offset:swizzle(SWAP,16)
	ds_swizzle_b32 v3, v208 offset:swizzle(SWAP,16)
	ds_swizzle_b32 v5, v209 offset:swizzle(SWAP,16)
	s_waitcnt lgkmcnt(0)
	v_add_f32_e32 v206, v206, v0
	v_add_f32_e32 v207, v207, v1
	v_add_f32_e32 v208, v208, v3
	v_add_f32_e32 v209, v209, v5
	v_mov_b32_e32 v0, v206
	v_mov_b32_e32 v1, v207
	v_mov_b32_e32 v3, v208
	v_mov_b32_e32 v5, v209
	s_nop 1
	v_permlane32_swap_b32_e32 v206, v0
	v_permlane32_swap_b32_e32 v207, v1
	v_permlane32_swap_b32_e32 v208, v3
	v_permlane32_swap_b32_e32 v209, v5
	s_nop 1
	s_mov_b64 vcc, exec
	s_mov_b64 exec, s[6:7]
	v_add_f32_e32 v206, v206, v0
	v_add_f32_e32 v207, v207, v1
	v_add_f32_e32 v208, v208, v3
	v_add_f32_e32 v209, v209, v5
	s_lshl_b32 s22, s20, 2
	s_add_u32 s24, s3, s22
	s_addc_u32 s25, s9, 0
	s_lshl_b32 s22, s29, 2
	global_store_dword v177, v206, s[24:25]
	s_add_u32 s24, s24, s22
	s_addc_u32 s25, s25, 0
	global_store_dword v177, v207, s[24:25]
	s_add_u32 s24, s24, s22
	s_addc_u32 s25, s25, 0
	global_store_dword v177, v208, s[24:25]
	s_add_u32 s24, s24, s22
	s_addc_u32 s25, s25, 0
	global_store_dword v177, v209, s[24:25]
	s_mov_b64 exec, vcc
	s_add_i32 s30, s30, 1
	s_add_i32 s28, s28, 1
	s_cmp_lt_u32 s30, 13
	s_cbranch_scc1 .Lbv_row
	s_cmp_gt_u32 s30, 13
	s_cbranch_scc1 .LBB0_605
	s_cmpk_ge_u32 s8, 0x400
	s_cbranch_scc1 .LBB0_605
	s_add_i32 s28, s8, 0x6800
	s_branch .Lbv_row
